# G4: per-row rs loads hoisted ahead of the K-loop, epilogue drain removed (on top of flat barrier second stage)
# speedup vs baseline: 1.0034x; 1.0034x over previous
.LBB0_311:
	s_waitcnt lgkmcnt(0)
	v_readlane_b32 s16, v254, 56
	v_readlane_b32 s4, v252, 14
	v_readlane_b32 s5, v252, 15
	v_mov_b32_e32 v4, 1
	v_mov_b32_e32 v6, s16
	ds_read_b32 v5, v6 offset:8
	s_nop 3
	global_atomic_add v4, v3, v4, s[4:5] sc0
	s_waitcnt vmcnt(0) lgkmcnt(0)
	v_add_u32_e32 v5, 1, v5
	v_mul_lo_u32 v1, v5, v2
	v_mul_lo_u32 v8, v5, v0
	v_add_u32_e32 v4, 1, v4
	ds_write_b32 v6, v5 offset:8
	v_readlane_b32 s4, v252, 18
	v_readlane_b32 s5, v252, 19
	v_readfirstlane_b32 s20, v1
	v_readfirstlane_b32 s21, v4
	v_readfirstlane_b32 s17, v8
	s_cmp_lg_u32 s21, s20
	s_cbranch_scc1 .Lxb0_poll
	buffer_wbl2 sc1
	s_waitcnt vmcnt(0)
	v_mov_b32_e32 v4, 1
	global_atomic_add v3, v4, s[4:5]

.LBB0_1097:
	s_add_u32 s2, s2, 0x40080
	s_addc_u32 s3, s3, 0
	s_add_u32 s9, s4, 0x100
	v_mov_b32_e32 v4, 0
	s_addc_u32 s11, s5, 0
	s_mov_b32 s53, -2
	v_mov_b32_e32 v5, v4
	v_mov_b32_e32 v6, v4
	v_mov_b32_e32 v7, v4
	v_mov_b32_e32 v8, v4
	v_mov_b32_e32 v9, v4
	v_mov_b32_e32 v10, v4
	v_mov_b32_e32 v11, v4
	v_mov_b32_e32 v12, v4
	v_mov_b32_e32 v13, v4
	v_mov_b32_e32 v14, v4
	v_mov_b32_e32 v15, v4
	v_mov_b32_e32 v16, v4
	v_mov_b32_e32 v17, v4
	v_mov_b32_e32 v18, v4
	v_mov_b32_e32 v19, v4
	v_mov_b32_e32 v20, v4
	v_mov_b32_e32 v21, v4
	v_mov_b32_e32 v22, v4
	v_mov_b32_e32 v23, v4
	v_mov_b32_e32 v24, v4
	v_mov_b32_e32 v25, v4
	v_mov_b32_e32 v26, v4
	v_mov_b32_e32 v27, v4
	v_mov_b32_e32 v28, v4
	v_mov_b32_e32 v29, v4
	v_mov_b32_e32 v30, v4
	v_mov_b32_e32 v31, v4
	v_mov_b32_e32 v32, v4
	v_mov_b32_e32 v33, v4
	v_mov_b32_e32 v34, v4
	v_mov_b32_e32 v35, v4
	v_mov_b32_e32 v60, v4
	v_mov_b32_e32 v61, v4
	v_mov_b32_e32 v62, v4
	v_mov_b32_e32 v63, v4
	v_mov_b32_e32 v64, v4
	v_mov_b32_e32 v65, v4
	v_mov_b32_e32 v66, v4
	v_mov_b32_e32 v67, v4
	v_mov_b32_e32 v76, v4
	v_mov_b32_e32 v77, v4
	v_mov_b32_e32 v78, v4
	v_mov_b32_e32 v79, v4
	v_mov_b32_e32 v80, v4
	v_mov_b32_e32 v81, v4
	v_mov_b32_e32 v82, v4
	v_mov_b32_e32 v83, v4
	v_mov_b32_e32 v84, v4
	v_mov_b32_e32 v85, v4
	v_mov_b32_e32 v86, v4
	v_mov_b32_e32 v87, v4
	v_mov_b32_e32 v88, v4
	v_mov_b32_e32 v89, v4
	v_mov_b32_e32 v90, v4
	v_mov_b32_e32 v91, v4
	v_mov_b32_e32 v92, v4
	v_mov_b32_e32 v93, v4
	v_mov_b32_e32 v94, v4
	v_mov_b32_e32 v95, v4
	v_mov_b32_e32 v96, v4
	v_mov_b32_e32 v97, v4
	v_mov_b32_e32 v98, v4
	v_mov_b32_e32 v99, v4
	v_mov_b32_e32 v36, v4
	v_mov_b32_e32 v37, v4
	v_mov_b32_e32 v38, v4
	v_mov_b32_e32 v39, v4
	v_mov_b32_e32 v40, v4
	v_mov_b32_e32 v41, v4
	v_mov_b32_e32 v42, v4
	v_mov_b32_e32 v43, v4
	v_mov_b32_e32 v44, v4
	v_mov_b32_e32 v45, v4
	v_mov_b32_e32 v46, v4
	v_mov_b32_e32 v47, v4
	v_mov_b32_e32 v48, v4
	v_mov_b32_e32 v49, v4
	v_mov_b32_e32 v50, v4
	v_mov_b32_e32 v51, v4
	v_mov_b32_e32 v52, v4
	v_mov_b32_e32 v53, v4
	v_mov_b32_e32 v54, v4
	v_mov_b32_e32 v55, v4
	v_mov_b32_e32 v56, v4
	v_mov_b32_e32 v57, v4
	v_mov_b32_e32 v58, v4
	v_mov_b32_e32 v59, v4
	v_mov_b32_e32 v68, v4
	v_mov_b32_e32 v69, v4
	v_mov_b32_e32 v70, v4
	v_mov_b32_e32 v71, v4
	v_mov_b32_e32 v72, v4
	v_mov_b32_e32 v73, v4
	v_mov_b32_e32 v74, v4
	v_mov_b32_e32 v75, v4
	v_mov_b32_e32 v100, v4
	v_mov_b32_e32 v101, v4
	v_mov_b32_e32 v102, v4
	v_mov_b32_e32 v103, v4
	v_mov_b32_e32 v104, v4
	v_mov_b32_e32 v105, v4
	v_mov_b32_e32 v106, v4
	v_mov_b32_e32 v107, v4
	v_mov_b32_e32 v108, v4
	v_mov_b32_e32 v109, v4
	v_mov_b32_e32 v110, v4
	v_mov_b32_e32 v111, v4
	v_mov_b32_e32 v112, v4
	v_mov_b32_e32 v113, v4
	v_mov_b32_e32 v114, v4
	v_mov_b32_e32 v115, v4
	v_mov_b32_e32 v116, v4
	v_mov_b32_e32 v117, v4
	v_mov_b32_e32 v118, v4
	v_mov_b32_e32 v119, v4
	v_mov_b32_e32 v120, v4
	v_mov_b32_e32 v121, v4
	v_mov_b32_e32 v122, v4
	v_mov_b32_e32 v123, v4
	v_mov_b32_e32 v124, v4
	v_mov_b32_e32 v125, v4
	v_mov_b32_e32 v126, v4
	v_mov_b32_e32 v127, v4
	v_mov_b32_e32 v128, v4
	v_mov_b32_e32 v129, v4
	v_mov_b32_e32 v130, v4
	v_mov_b32_e32 v131, v4
	v_lshl_add_u32 v171, s37, 8, v156
	v_lshlrev_b32_e32 v171, 2, v171
	global_load_dword v164, v171, s[70:71]
	global_load_dword v165, v171, s[70:71] offset:64
	global_load_dword v166, v171, s[70:71] offset:128
	global_load_dword v167, v171, s[70:71] offset:192
	global_load_dword v246, v171, s[70:71] offset:512
	global_load_dword v247, v171, s[70:71] offset:576
	global_load_dword v248, v171, s[70:71] offset:640
	global_load_dword v249, v171, s[70:71] offset:704
.LBB0_1098:
	s_add_u32 s4, s2, 0xfffc0080
	s_addc_u32 s5, s3, -1
	s_add_i32 s72, 0, 0x10000
	v_add_u32_e32 v152, s72, v157
	ds_read_b128 v[140:143], v152
	ds_read_b128 v[144:147], v152 offset:1024
	ds_read_b128 v[148:151], v152 offset:2048
	ds_read_b128 v[152:155], v152 offset:3072
	s_cmp_eq_u32 s53, 12
	s_cselect_b32 s17, s49, s5
	s_cselect_b32 s16, s48, s4
	s_cselect_b32 s5, s21, s11
	s_cselect_b32 s4, s20, s9
	v_lshl_add_u64 v[168:169], s[2:3], 0, v[136:137]
	s_add_i32 m0, s26, 0xc000
	ds_read_b128 v[160:163], v159
	ds_read_b128 v[172:175], v159 offset:1024
	ds_read_b128 v[176:179], v159 offset:2048
	ds_read_b128 v[180:183], v159 offset:3072
	ds_read_b128 v[184:187], v159 offset:4096
	ds_read_b128 v[188:191], v159 offset:5120
	ds_read_b128 v[192:195], v159 offset:6144
	ds_read_b128 v[196:199], v159 offset:7168
	global_load_lds_dwordx4 v[168:169], off
	v_lshl_add_u64 v[168:169], s[2:3], 0, v[138:139]
	s_add_i32 m0, s26, 0xe000
	s_nop 0
	global_load_lds_dwordx4 v[168:169], off
	s_waitcnt lgkmcnt(8)
	s_barrier
	s_waitcnt lgkmcnt(0)
	s_waitcnt lgkmcnt(0)
	v_mfma_f32_16x16x32_bf16 v[128:131], v[140:143], v[160:163], v[128:131]
	v_mfma_f32_16x16x32_bf16 v[124:127], v[148:151], v[160:163], v[124:127]
	v_mfma_f32_16x16x32_bf16 v[120:123], v[140:143], v[176:179], v[120:123]
	v_mfma_f32_16x16x32_bf16 v[116:119], v[148:151], v[176:179], v[116:119]
	v_mfma_f32_16x16x32_bf16 v[112:115], v[140:143], v[184:187], v[112:115]
	v_mfma_f32_16x16x32_bf16 v[108:111], v[148:151], v[184:187], v[108:111]
	v_mfma_f32_16x16x32_bf16 v[104:107], v[140:143], v[192:195], v[104:107]
	v_mfma_f32_16x16x32_bf16 v[100:103], v[148:151], v[192:195], v[100:103]
	v_mfma_f32_16x16x32_bf16 v[128:131], v[144:147], v[172:175], v[128:131]
	v_mfma_f32_16x16x32_bf16 v[124:127], v[152:155], v[172:175], v[124:127]
	v_mfma_f32_16x16x32_bf16 v[120:123], v[144:147], v[180:183], v[120:123]
	v_mfma_f32_16x16x32_bf16 v[116:119], v[152:155], v[180:183], v[116:119]
	v_mfma_f32_16x16x32_bf16 v[112:115], v[144:147], v[188:191], v[112:115]
	v_mfma_f32_16x16x32_bf16 v[108:111], v[152:155], v[188:191], v[108:111]
	v_mfma_f32_16x16x32_bf16 v[104:107], v[144:147], v[196:199], v[104:107]
	v_mfma_f32_16x16x32_bf16 v[100:103], v[152:155], v[196:199], v[100:103]
	s_barrier
	s_add_i32 s74, 0, 0x14000
	v_add_u32_e32 v168, s74, v157
	s_add_i32 s72, s72, s23
	ds_read_b128 v[200:203], v168
	ds_read_b128 v[204:207], v168 offset:1024
	ds_read_b128 v[208:211], v168 offset:2048
	ds_read_b128 v[220:223], v168 offset:3072
	v_lshl_add_u64 v[168:169], s[4:5], 0, v[2:3]
	s_mov_b32 m0, s72
	v_lshl_add_u64 v[214:215], s[4:5], 0, v[0:1]
	global_load_lds_dwordx4 v[168:169], off
	s_add_i32 m0, s72, 0x2000
	s_nop 0
	global_load_lds_dwordx4 v[214:215], off
	s_barrier
	s_waitcnt lgkmcnt(0)
	s_waitcnt lgkmcnt(0)
	v_mfma_f32_16x16x32_bf16 v[72:75], v[200:203], v[160:163], v[72:75]
	v_mfma_f32_16x16x32_bf16 v[68:71], v[208:211], v[160:163], v[68:71]
	v_mfma_f32_16x16x32_bf16 v[56:59], v[200:203], v[176:179], v[56:59]
	v_mfma_f32_16x16x32_bf16 v[52:55], v[208:211], v[176:179], v[52:55]
	v_mfma_f32_16x16x32_bf16 v[48:51], v[200:203], v[184:187], v[48:51]
	v_mfma_f32_16x16x32_bf16 v[44:47], v[208:211], v[184:187], v[44:47]
	v_mfma_f32_16x16x32_bf16 v[40:43], v[200:203], v[192:195], v[40:43]
	v_mfma_f32_16x16x32_bf16 v[36:39], v[208:211], v[192:195], v[36:39]
	v_mfma_f32_16x16x32_bf16 v[72:75], v[204:207], v[172:175], v[72:75]
	v_mfma_f32_16x16x32_bf16 v[68:71], v[220:223], v[172:175], v[68:71]
	v_mfma_f32_16x16x32_bf16 v[56:59], v[204:207], v[180:183], v[56:59]
	v_mfma_f32_16x16x32_bf16 v[52:55], v[220:223], v[180:183], v[52:55]
	v_mfma_f32_16x16x32_bf16 v[48:51], v[204:207], v[188:191], v[48:51]
	v_mfma_f32_16x16x32_bf16 v[44:47], v[220:223], v[188:191], v[44:47]
	v_mfma_f32_16x16x32_bf16 v[40:43], v[204:207], v[196:199], v[40:43]
	v_mfma_f32_16x16x32_bf16 v[36:39], v[220:223], v[196:199], v[36:39]
	s_mov_b32 m0, s26
	v_lshl_add_u64 v[224:225], s[16:17], 0, v[134:135]
	s_barrier
	ds_read_b128 v[160:163], v159 offset:16384
	ds_read_b128 v[172:175], v159 offset:17408
	ds_read_b128 v[176:179], v159 offset:18432
	ds_read_b128 v[180:183], v159 offset:19456
	ds_read_b128 v[184:187], v159 offset:20480
	ds_read_b128 v[188:191], v159 offset:21504
	ds_read_b128 v[192:195], v159 offset:22528
	ds_read_b128 v[196:199], v159 offset:23552
	global_load_lds_dwordx4 v[224:225], off
	v_lshl_add_u64 v[234:235], s[16:17], 0, v[132:133]
	s_mov_b32 m0, s27
	s_nop 0
	global_load_lds_dwordx4 v[234:235], off
	s_barrier
	s_waitcnt lgkmcnt(0)
	s_waitcnt lgkmcnt(0)
	v_mfma_f32_16x16x32_bf16 v[96:99], v[140:143], v[160:163], v[96:99]
	v_mfma_f32_16x16x32_bf16 v[92:95], v[148:151], v[160:163], v[92:95]
	v_mfma_f32_16x16x32_bf16 v[88:91], v[140:143], v[176:179], v[88:91]
	v_mfma_f32_16x16x32_bf16 v[84:87], v[148:151], v[176:179], v[84:87]
	v_mfma_f32_16x16x32_bf16 v[80:83], v[140:143], v[184:187], v[80:83]
	v_mfma_f32_16x16x32_bf16 v[76:79], v[148:151], v[184:187], v[76:79]
	v_mfma_f32_16x16x32_bf16 v[64:67], v[140:143], v[192:195], v[64:67]
	v_mfma_f32_16x16x32_bf16 v[60:63], v[148:151], v[192:195], v[60:63]
	v_mfma_f32_16x16x32_bf16 v[96:99], v[144:147], v[172:175], v[96:99]
	v_mfma_f32_16x16x32_bf16 v[92:95], v[152:155], v[172:175], v[92:95]
	v_mfma_f32_16x16x32_bf16 v[88:91], v[144:147], v[180:183], v[88:91]
	v_mfma_f32_16x16x32_bf16 v[84:87], v[152:155], v[180:183], v[84:87]
	v_mfma_f32_16x16x32_bf16 v[80:83], v[144:147], v[188:191], v[80:83]
	v_mfma_f32_16x16x32_bf16 v[76:79], v[152:155], v[188:191], v[76:79]
	v_mfma_f32_16x16x32_bf16 v[64:67], v[144:147], v[196:199], v[64:67]
	v_mfma_f32_16x16x32_bf16 v[60:63], v[152:155], v[196:199], v[60:63]
	s_barrier
	s_add_u32 s72, s4, 0x40000
	s_addc_u32 s73, s5, 0
	s_add_i32 s74, s74, s23
	v_lshl_add_u64 v[140:141], s[72:73], 0, v[2:3]
	s_mov_b32 m0, s74
	s_nop 0
	global_load_lds_dwordx4 v[140:141], off
	v_lshl_add_u64 v[140:141], s[72:73], 0, v[0:1]
	s_add_i32 m0, s74, 0x2000
	s_nop 0
	global_load_lds_dwordx4 v[140:141], off
	s_waitcnt vmcnt(6)
	s_barrier
	v_mfma_f32_16x16x32_bf16 v[32:35], v[200:203], v[160:163], v[32:35]
	v_mfma_f32_16x16x32_bf16 v[28:31], v[208:211], v[160:163], v[28:31]
	v_mfma_f32_16x16x32_bf16 v[24:27], v[200:203], v[176:179], v[24:27]
	v_mfma_f32_16x16x32_bf16 v[20:23], v[208:211], v[176:179], v[20:23]
	v_mfma_f32_16x16x32_bf16 v[16:19], v[200:203], v[184:187], v[16:19]
	v_mfma_f32_16x16x32_bf16 v[12:15], v[208:211], v[184:187], v[12:15]
	v_mfma_f32_16x16x32_bf16 v[8:11], v[200:203], v[192:195], v[8:11]
	v_mfma_f32_16x16x32_bf16 v[4:7], v[208:211], v[192:195], v[4:7]
	v_mfma_f32_16x16x32_bf16 v[32:35], v[204:207], v[172:175], v[32:35]
	v_mfma_f32_16x16x32_bf16 v[28:31], v[220:223], v[172:175], v[28:31]
	v_mfma_f32_16x16x32_bf16 v[24:27], v[204:207], v[180:183], v[24:27]
	v_mfma_f32_16x16x32_bf16 v[20:23], v[220:223], v[180:183], v[20:23]
	v_mfma_f32_16x16x32_bf16 v[16:19], v[204:207], v[188:191], v[16:19]
	v_mfma_f32_16x16x32_bf16 v[12:15], v[220:223], v[188:191], v[12:15]
	v_mfma_f32_16x16x32_bf16 v[8:11], v[204:207], v[196:199], v[8:11]
	v_mfma_f32_16x16x32_bf16 v[4:7], v[220:223], v[196:199], v[4:7]
	s_add_i32 s72, 0, 0x18000
	v_add_u32_e32 v152, s72, v157
	s_barrier
	ds_read_b128 v[140:143], v152
	ds_read_b128 v[144:147], v152 offset:1024
	ds_read_b128 v[148:151], v152 offset:2048
	ds_read_b128 v[152:155], v152 offset:3072
	s_add_u32 s16, s16, 0x40000
	s_addc_u32 s17, s17, 0
	s_mov_b32 m0, s30
	v_lshl_add_u64 v[200:201], s[16:17], 0, v[134:135]
	ds_read_b128 v[160:163], v159 offset:32768
	ds_read_b128 v[172:175], v159 offset:33792
	ds_read_b128 v[176:179], v159 offset:34816
	ds_read_b128 v[180:183], v159 offset:35840
	ds_read_b128 v[184:187], v159 offset:36864
	ds_read_b128 v[188:191], v159 offset:37888
	ds_read_b128 v[192:195], v159 offset:38912
	ds_read_b128 v[196:199], v159 offset:39936
	global_load_lds_dwordx4 v[200:201], off
	v_lshl_add_u64 v[200:201], s[16:17], 0, v[132:133]
	s_mov_b32 m0, s31
	s_nop 0
	global_load_lds_dwordx4 v[200:201], off
	s_waitcnt lgkmcnt(8)
	s_barrier
	s_waitcnt lgkmcnt(0)
	s_waitcnt lgkmcnt(0)
	v_mfma_f32_16x16x32_bf16 v[128:131], v[140:143], v[160:163], v[128:131]
	v_mfma_f32_16x16x32_bf16 v[124:127], v[148:151], v[160:163], v[124:127]
	v_mfma_f32_16x16x32_bf16 v[120:123], v[140:143], v[176:179], v[120:123]
	v_mfma_f32_16x16x32_bf16 v[116:119], v[148:151], v[176:179], v[116:119]
	v_mfma_f32_16x16x32_bf16 v[112:115], v[140:143], v[184:187], v[112:115]
	v_mfma_f32_16x16x32_bf16 v[108:111], v[148:151], v[184:187], v[108:111]
	v_mfma_f32_16x16x32_bf16 v[104:107], v[140:143], v[192:195], v[104:107]
	v_mfma_f32_16x16x32_bf16 v[100:103], v[148:151], v[192:195], v[100:103]
	v_mfma_f32_16x16x32_bf16 v[128:131], v[144:147], v[172:175], v[128:131]
	v_mfma_f32_16x16x32_bf16 v[124:127], v[152:155], v[172:175], v[124:127]
	v_mfma_f32_16x16x32_bf16 v[120:123], v[144:147], v[180:183], v[120:123]
	v_mfma_f32_16x16x32_bf16 v[116:119], v[152:155], v[180:183], v[116:119]
	v_mfma_f32_16x16x32_bf16 v[112:115], v[144:147], v[188:191], v[112:115]
	v_mfma_f32_16x16x32_bf16 v[108:111], v[152:155], v[188:191], v[108:111]
	v_mfma_f32_16x16x32_bf16 v[104:107], v[144:147], v[196:199], v[104:107]
	v_mfma_f32_16x16x32_bf16 v[100:103], v[152:155], v[196:199], v[100:103]
	s_barrier
	s_add_i32 s16, 0, 0x1c000
	s_add_i32 s17, s72, s23
	v_add_u32_e32 v170, s16, v157
	v_lshl_add_u64 v[168:169], v[168:169], 0, s[28:29]
	s_mov_b32 m0, s17
	ds_read_b128 v[200:203], v170
	ds_read_b128 v[204:207], v170 offset:1024
	ds_read_b128 v[208:211], v170 offset:2048
	ds_read_b128 v[220:223], v170 offset:3072
	global_load_lds_dwordx4 v[168:169], off
	v_lshl_add_u64 v[168:169], v[214:215], 0, s[28:29]
	s_add_i32 m0, s17, 0x2000
	s_nop 0
	global_load_lds_dwordx4 v[168:169], off
	s_barrier
	s_waitcnt lgkmcnt(0)
	s_waitcnt lgkmcnt(0)
	v_mfma_f32_16x16x32_bf16 v[72:75], v[200:203], v[160:163], v[72:75]
	v_mfma_f32_16x16x32_bf16 v[68:71], v[208:211], v[160:163], v[68:71]
	v_mfma_f32_16x16x32_bf16 v[56:59], v[200:203], v[176:179], v[56:59]
	v_mfma_f32_16x16x32_bf16 v[52:55], v[208:211], v[176:179], v[52:55]
	v_mfma_f32_16x16x32_bf16 v[48:51], v[200:203], v[184:187], v[48:51]
	v_mfma_f32_16x16x32_bf16 v[44:47], v[208:211], v[184:187], v[44:47]
	v_mfma_f32_16x16x32_bf16 v[40:43], v[200:203], v[192:195], v[40:43]
	v_mfma_f32_16x16x32_bf16 v[36:39], v[208:211], v[192:195], v[36:39]
	v_mfma_f32_16x16x32_bf16 v[72:75], v[204:207], v[172:175], v[72:75]
	v_mfma_f32_16x16x32_bf16 v[68:71], v[220:223], v[172:175], v[68:71]
	v_mfma_f32_16x16x32_bf16 v[56:59], v[204:207], v[180:183], v[56:59]
	v_mfma_f32_16x16x32_bf16 v[52:55], v[220:223], v[180:183], v[52:55]
	v_mfma_f32_16x16x32_bf16 v[48:51], v[204:207], v[188:191], v[48:51]
	v_mfma_f32_16x16x32_bf16 v[44:47], v[220:223], v[188:191], v[44:47]
	v_mfma_f32_16x16x32_bf16 v[40:43], v[204:207], v[196:199], v[40:43]
	v_mfma_f32_16x16x32_bf16 v[36:39], v[220:223], v[196:199], v[36:39]
	s_mov_b32 m0, s50
	v_lshl_add_u64 v[168:169], v[224:225], 0, s[28:29]
	s_barrier
	ds_read_b128 v[160:163], v159 offset:49152
	ds_read_b128 v[172:175], v159 offset:50176
	ds_read_b128 v[176:179], v159 offset:51200
	ds_read_b128 v[180:183], v159 offset:52224
	ds_read_b128 v[184:187], v159 offset:53248
	ds_read_b128 v[188:191], v159 offset:54272
	ds_read_b128 v[192:195], v159 offset:55296
	ds_read_b128 v[196:199], v159 offset:56320
	global_load_lds_dwordx4 v[168:169], off
	v_lshl_add_u64 v[168:169], v[234:235], 0, s[28:29]
	s_mov_b32 m0, s51
	s_nop 0
	global_load_lds_dwordx4 v[168:169], off
	s_barrier
	s_waitcnt lgkmcnt(0)
	s_waitcnt lgkmcnt(0)
	v_mfma_f32_16x16x32_bf16 v[96:99], v[140:143], v[160:163], v[96:99]
	v_mfma_f32_16x16x32_bf16 v[92:95], v[148:151], v[160:163], v[92:95]
	v_mfma_f32_16x16x32_bf16 v[88:91], v[140:143], v[176:179], v[88:91]
	v_mfma_f32_16x16x32_bf16 v[84:87], v[148:151], v[176:179], v[84:87]
	v_mfma_f32_16x16x32_bf16 v[80:83], v[140:143], v[184:187], v[80:83]
	v_mfma_f32_16x16x32_bf16 v[76:79], v[148:151], v[184:187], v[76:79]
	v_mfma_f32_16x16x32_bf16 v[64:67], v[140:143], v[192:195], v[64:67]
	v_mfma_f32_16x16x32_bf16 v[60:63], v[148:151], v[192:195], v[60:63]
	v_mfma_f32_16x16x32_bf16 v[96:99], v[144:147], v[172:175], v[96:99]
	v_mfma_f32_16x16x32_bf16 v[92:95], v[152:155], v[172:175], v[92:95]
	v_mfma_f32_16x16x32_bf16 v[88:91], v[144:147], v[180:183], v[88:91]
	v_mfma_f32_16x16x32_bf16 v[84:87], v[152:155], v[180:183], v[84:87]
	v_mfma_f32_16x16x32_bf16 v[80:83], v[144:147], v[188:191], v[80:83]
	v_mfma_f32_16x16x32_bf16 v[76:79], v[152:155], v[188:191], v[76:79]
	v_mfma_f32_16x16x32_bf16 v[64:67], v[144:147], v[196:199], v[64:67]
	v_mfma_f32_16x16x32_bf16 v[60:63], v[152:155], v[196:199], v[60:63]
	s_barrier
	s_add_u32 s4, s4, 0x40080
	s_addc_u32 s5, s5, 0
	s_add_i32 s16, s16, s23
	v_lshl_add_u64 v[140:141], s[4:5], 0, v[2:3]
	s_mov_b32 m0, s16
	s_nop 0
	global_load_lds_dwordx4 v[140:141], off
	v_lshl_add_u64 v[140:141], s[4:5], 0, v[0:1]
	s_add_i32 m0, s16, 0x2000
	s_nop 0
	global_load_lds_dwordx4 v[140:141], off
	s_waitcnt vmcnt(6)
	s_barrier
	v_mfma_f32_16x16x32_bf16 v[32:35], v[200:203], v[160:163], v[32:35]
	v_mfma_f32_16x16x32_bf16 v[28:31], v[208:211], v[160:163], v[28:31]
	v_mfma_f32_16x16x32_bf16 v[24:27], v[200:203], v[176:179], v[24:27]
	v_mfma_f32_16x16x32_bf16 v[20:23], v[208:211], v[176:179], v[20:23]
	v_mfma_f32_16x16x32_bf16 v[16:19], v[200:203], v[184:187], v[16:19]
	v_mfma_f32_16x16x32_bf16 v[12:15], v[208:211], v[184:187], v[12:15]
	v_mfma_f32_16x16x32_bf16 v[8:11], v[200:203], v[192:195], v[8:11]
	v_mfma_f32_16x16x32_bf16 v[4:7], v[208:211], v[192:195], v[4:7]
	v_mfma_f32_16x16x32_bf16 v[32:35], v[204:207], v[172:175], v[32:35]
	v_mfma_f32_16x16x32_bf16 v[28:31], v[220:223], v[172:175], v[28:31]
	v_mfma_f32_16x16x32_bf16 v[24:27], v[204:207], v[180:183], v[24:27]
	v_mfma_f32_16x16x32_bf16 v[20:23], v[220:223], v[180:183], v[20:23]
	v_mfma_f32_16x16x32_bf16 v[16:19], v[204:207], v[188:191], v[16:19]
	v_mfma_f32_16x16x32_bf16 v[12:15], v[220:223], v[188:191], v[12:15]
	v_mfma_f32_16x16x32_bf16 v[8:11], v[204:207], v[196:199], v[8:11]
	v_mfma_f32_16x16x32_bf16 v[4:7], v[220:223], v[196:199], v[4:7]
	s_add_i32 s53, s53, 2
	s_add_u32 s2, s2, 0x100
	s_addc_u32 s3, s3, 0
	s_add_u32 s9, s9, 0x100
	s_addc_u32 s11, s11, 0
	s_cmp_gt_u32 s53, 13
	s_barrier
	s_cbranch_scc0 .LBB0_1098
	v_lshl_add_u32 v154, s37, 8, v156
	v_ashrrev_i32_e32 v155, 31, v154
	v_lshl_add_u64 v[168:169], v[154:155], 2, s[70:71]
	v_mov_b32_e32 v174, v164
	v_mov_b32_e32 v173, v165
	v_mov_b32_e32 v172, v166
	v_mov_b32_e32 v170, v167
	v_mov_b32_e32 v163, v246
	v_mov_b32_e32 v162, v247
	v_mov_b32_e32 v161, v248
	v_mov_b32_e32 v160, v249
	v_lshl_or_b32 v168, s36, 8, v158
	v_ashrrev_i32_e32 v169, 31, v168
	v_or_b32_e32 v152, 16, v154
	v_ashrrev_i32_e32 v153, 31, v152
	v_or_b32_e32 v150, 32, v154
	v_ashrrev_i32_e32 v151, 31, v150
	v_or_b32_e32 v148, 48, v154
	v_ashrrev_i32_e32 v149, 31, v148
	v_add_u32_e32 v146, 0x80, v154
	v_ashrrev_i32_e32 v147, 31, v146
	v_add_u32_e32 v144, 0x90, v154
	v_ashrrev_i32_e32 v145, 31, v144
	v_add_u32_e32 v142, 0xa0, v154
	v_ashrrev_i32_e32 v143, 31, v142
	v_add_u32_e32 v140, 0xb0, v154
	v_ashrrev_i32_e32 v141, 31, v140
	v_readlane_b32 s72, v255, 28
	s_and_b64 vcc, exec, s[46:47]
	s_mov_b32 s36, s8
	s_mov_b32 s37, s10
	s_mov_b64 s[4:5], s[20:21]
	s_mov_b64 s[2:3], s[48:49]
	v_readlane_b32 s73, v255, 29
	v_mul_f32_e32 v124, v124, v174
	v_mul_f32_e32 v125, v125, v174
	v_max_f32_e32 v124, 0, v124
	v_max_f32_e32 v125, 0, v125
	v_pk_mul_f32 v[176:177], v[124:125], v[124:125]
	v_mul_f32_e32 v125, v126, v174
	v_mul_f32_e32 v124, v174, v130
	v_max_f32_e32 v126, 0, v125
	v_mul_f32_e32 v125, v174, v131
	v_mul_f32_e32 v128, v174, v128
	v_mul_f32_e32 v129, v174, v129
	v_max_f32_e32 v124, 0, v124
	v_max_f32_e32 v125, 0, v125
	v_mul_f32_e32 v127, v127, v174
	v_max_f32_e32 v128, 0, v128
	v_max_f32_e32 v129, 0, v129
	v_max_f32_e32 v127, 0, v127
	v_pk_mul_f32 v[130:131], v[124:125], v[124:125]
	v_lshlrev_b64 v[124:125], 13, v[154:155]
	v_pk_mul_f32 v[128:129], v[128:129], v[128:129]
	v_pk_mul_f32 v[178:179], v[126:127], v[126:127]
	v_lshl_add_u64 v[124:125], s[94:95], 0, v[124:125]
	v_lshlrev_b64 v[126:127], 1, v[168:169]
	v_mul_f32_e32 v116, v116, v173
	v_mul_f32_e32 v117, v117, v173
	v_lshl_add_u64 v[124:125], v[124:125], 0, v[126:127]
	v_cvt_pk_bf16_f32 v128, v128, v129
	v_cvt_pk_bf16_f32 v129, v130, v131
	v_cvt_pk_bf16_f32 v130, v176, v177
	v_cvt_pk_bf16_f32 v131, v178, v179
	v_max_f32_e32 v116, 0, v116
	v_max_f32_e32 v117, 0, v117
	global_store_dwordx4 v[124:125], v[128:131], off
	v_mul_f32_e32 v120, v120, v173
	v_mul_f32_e32 v121, v121, v173
	v_pk_mul_f32 v[128:129], v[116:117], v[116:117]
	v_mul_f32_e32 v117, v118, v173
	v_mul_f32_e32 v116, v122, v173
	v_max_f32_e32 v118, 0, v117
	v_mul_f32_e32 v117, v123, v173
	v_max_f32_e32 v116, 0, v116
	v_max_f32_e32 v117, 0, v117
	v_mul_f32_e32 v119, v119, v173
	v_max_f32_e32 v120, 0, v120
	v_max_f32_e32 v121, 0, v121
	v_max_f32_e32 v119, 0, v119
	v_pk_mul_f32 v[122:123], v[116:117], v[116:117]
	v_lshlrev_b64 v[116:117], 13, v[152:153]
	v_pk_mul_f32 v[120:121], v[120:121], v[120:121]
	v_pk_mul_f32 v[130:131], v[118:119], v[118:119]
	v_lshl_add_u64 v[116:117], s[94:95], 0, v[116:117]
	v_mul_f32_e32 v108, v108, v172
	v_mul_f32_e32 v109, v109, v172
	v_lshl_add_u64 v[116:117], v[116:117], 0, v[126:127]
	v_cvt_pk_bf16_f32 v118, v120, v121
	v_cvt_pk_bf16_f32 v119, v122, v123
	v_cvt_pk_bf16_f32 v120, v128, v129
	v_cvt_pk_bf16_f32 v121, v130, v131
	v_max_f32_e32 v108, 0, v108
	v_max_f32_e32 v109, 0, v109
	global_store_dwordx4 v[116:117], v[118:121], off
	v_mul_f32_e32 v112, v112, v172
	v_mul_f32_e32 v113, v113, v172
	v_pk_mul_f32 v[118:119], v[108:109], v[108:109]
	v_mul_f32_e32 v109, v110, v172
	v_mul_f32_e32 v108, v114, v172
	v_max_f32_e32 v110, 0, v109
	v_mul_f32_e32 v109, v115, v172
	v_max_f32_e32 v108, 0, v108
	v_max_f32_e32 v109, 0, v109
	v_mul_f32_e32 v111, v111, v172
	v_max_f32_e32 v112, 0, v112
	v_max_f32_e32 v113, 0, v113
	v_max_f32_e32 v111, 0, v111
	v_pk_mul_f32 v[114:115], v[108:109], v[108:109]
	v_lshlrev_b64 v[108:109], 13, v[150:151]
	v_pk_mul_f32 v[112:113], v[112:113], v[112:113]
	v_pk_mul_f32 v[120:121], v[110:111], v[110:111]
	v_lshl_add_u64 v[108:109], s[94:95], 0, v[108:109]
	v_mul_f32_e32 v100, v100, v170
	v_mul_f32_e32 v101, v101, v170
	v_lshl_add_u64 v[108:109], v[108:109], 0, v[126:127]
	v_cvt_pk_bf16_f32 v110, v112, v113
	v_cvt_pk_bf16_f32 v111, v114, v115
	v_cvt_pk_bf16_f32 v112, v118, v119
	v_cvt_pk_bf16_f32 v113, v120, v121
	v_max_f32_e32 v100, 0, v100
	v_max_f32_e32 v101, 0, v101
	global_store_dwordx4 v[108:109], v[110:113], off
	v_mul_f32_e32 v104, v104, v170
	v_mul_f32_e32 v105, v105, v170
	v_pk_mul_f32 v[110:111], v[100:101], v[100:101]
	v_mul_f32_e32 v101, v102, v170
	v_mul_f32_e32 v100, v106, v170
	v_max_f32_e32 v102, 0, v101
	v_mul_f32_e32 v101, v107, v170
	v_max_f32_e32 v100, 0, v100
	v_max_f32_e32 v101, 0, v101
	v_mul_f32_e32 v103, v103, v170
	v_max_f32_e32 v104, 0, v104
	v_max_f32_e32 v105, 0, v105
	v_max_f32_e32 v103, 0, v103
	v_pk_mul_f32 v[106:107], v[100:101], v[100:101]
	v_lshlrev_b64 v[100:101], 13, v[148:149]
	v_pk_mul_f32 v[104:105], v[104:105], v[104:105]
	v_pk_mul_f32 v[112:113], v[102:103], v[102:103]
	v_lshl_add_u64 v[100:101], s[94:95], 0, v[100:101]
	v_mul_f32_e32 v92, v92, v163
	v_mul_f32_e32 v93, v93, v163
	v_lshl_add_u64 v[100:101], v[100:101], 0, v[126:127]
	v_cvt_pk_bf16_f32 v102, v104, v105
	v_cvt_pk_bf16_f32 v103, v106, v107
	v_cvt_pk_bf16_f32 v104, v110, v111
	v_cvt_pk_bf16_f32 v105, v112, v113
	v_max_f32_e32 v92, 0, v92
	v_max_f32_e32 v93, 0, v93
	global_store_dwordx4 v[100:101], v[102:105], off
	v_mul_f32_e32 v96, v96, v163
	v_mul_f32_e32 v97, v97, v163
	v_pk_mul_f32 v[102:103], v[92:93], v[92:93]
	v_mul_f32_e32 v93, v94, v163
	v_mul_f32_e32 v92, v98, v163
	v_max_f32_e32 v94, 0, v93
	v_mul_f32_e32 v93, v99, v163
	v_max_f32_e32 v92, 0, v92
	v_max_f32_e32 v93, 0, v93
	v_mul_f32_e32 v95, v95, v163
	v_max_f32_e32 v96, 0, v96
	v_max_f32_e32 v97, 0, v97
	v_max_f32_e32 v95, 0, v95
	v_pk_mul_f32 v[98:99], v[92:93], v[92:93]
	v_lshlrev_b64 v[92:93], 13, v[146:147]
	v_pk_mul_f32 v[96:97], v[96:97], v[96:97]
	v_pk_mul_f32 v[104:105], v[94:95], v[94:95]
	v_lshl_add_u64 v[92:93], s[94:95], 0, v[92:93]
	v_mul_f32_e32 v84, v84, v162
	v_mul_f32_e32 v85, v85, v162
	v_lshl_add_u64 v[92:93], v[92:93], 0, v[126:127]
	v_cvt_pk_bf16_f32 v94, v96, v97
	v_cvt_pk_bf16_f32 v95, v98, v99
	v_cvt_pk_bf16_f32 v96, v102, v103
	v_cvt_pk_bf16_f32 v97, v104, v105
	v_max_f32_e32 v84, 0, v84
	v_max_f32_e32 v85, 0, v85
	global_store_dwordx4 v[92:93], v[94:97], off
	v_mul_f32_e32 v88, v88, v162
	v_mul_f32_e32 v89, v89, v162
	v_pk_mul_f32 v[94:95], v[84:85], v[84:85]
	v_mul_f32_e32 v85, v86, v162
	v_mul_f32_e32 v84, v90, v162
	v_max_f32_e32 v86, 0, v85
	v_mul_f32_e32 v85, v91, v162
	v_max_f32_e32 v84, 0, v84
	v_max_f32_e32 v85, 0, v85
	v_mul_f32_e32 v87, v87, v162
	v_max_f32_e32 v88, 0, v88
	v_max_f32_e32 v89, 0, v89
	v_max_f32_e32 v87, 0, v87
	v_pk_mul_f32 v[90:91], v[84:85], v[84:85]
	v_lshlrev_b64 v[84:85], 13, v[144:145]
	v_pk_mul_f32 v[88:89], v[88:89], v[88:89]
	v_pk_mul_f32 v[96:97], v[86:87], v[86:87]
	v_lshl_add_u64 v[84:85], s[94:95], 0, v[84:85]
	v_mul_f32_e32 v76, v76, v161
	v_mul_f32_e32 v77, v77, v161
	v_lshl_add_u64 v[84:85], v[84:85], 0, v[126:127]
	v_cvt_pk_bf16_f32 v86, v88, v89
	v_cvt_pk_bf16_f32 v87, v90, v91
	v_cvt_pk_bf16_f32 v88, v94, v95
	v_cvt_pk_bf16_f32 v89, v96, v97
	v_max_f32_e32 v76, 0, v76
	v_max_f32_e32 v77, 0, v77
	global_store_dwordx4 v[84:85], v[86:89], off
	v_mul_f32_e32 v80, v80, v161
	v_mul_f32_e32 v81, v81, v161
	v_pk_mul_f32 v[86:87], v[76:77], v[76:77]
	v_mul_f32_e32 v77, v78, v161
	v_mul_f32_e32 v76, v82, v161
	v_max_f32_e32 v78, 0, v77
	v_mul_f32_e32 v77, v83, v161
	v_max_f32_e32 v76, 0, v76
	v_max_f32_e32 v77, 0, v77
	v_mul_f32_e32 v79, v79, v161
	v_max_f32_e32 v80, 0, v80
	v_max_f32_e32 v81, 0, v81
	v_max_f32_e32 v79, 0, v79
	v_pk_mul_f32 v[82:83], v[76:77], v[76:77]
	v_lshlrev_b64 v[76:77], 13, v[142:143]
	v_pk_mul_f32 v[80:81], v[80:81], v[80:81]
	v_pk_mul_f32 v[88:89], v[78:79], v[78:79]
	v_lshl_add_u64 v[76:77], s[94:95], 0, v[76:77]
	v_mul_f32_e32 v60, v60, v160
	v_mul_f32_e32 v61, v61, v160
	v_lshl_add_u64 v[76:77], v[76:77], 0, v[126:127]
	v_cvt_pk_bf16_f32 v78, v80, v81
	v_cvt_pk_bf16_f32 v79, v82, v83
	v_cvt_pk_bf16_f32 v80, v86, v87
	v_cvt_pk_bf16_f32 v81, v88, v89
	v_max_f32_e32 v60, 0, v60
	v_max_f32_e32 v61, 0, v61
	global_store_dwordx4 v[76:77], v[78:81], off
	v_mul_f32_e32 v64, v64, v160
	v_mul_f32_e32 v65, v65, v160
	v_pk_mul_f32 v[78:79], v[60:61], v[60:61]
	v_mul_f32_e32 v61, v62, v160
	v_mul_f32_e32 v60, v66, v160
	v_max_f32_e32 v62, 0, v61
	v_mul_f32_e32 v61, v67, v160
	v_max_f32_e32 v60, 0, v60
	v_max_f32_e32 v61, 0, v61
	v_mul_f32_e32 v63, v63, v160
	v_max_f32_e32 v64, 0, v64
	v_max_f32_e32 v65, 0, v65
	v_max_f32_e32 v63, 0, v63
	v_pk_mul_f32 v[66:67], v[60:61], v[60:61]
	v_lshlrev_b64 v[60:61], 13, v[140:141]
	v_pk_mul_f32 v[64:65], v[64:65], v[64:65]
	v_pk_mul_f32 v[80:81], v[62:63], v[62:63]
	v_lshl_add_u64 v[60:61], s[94:95], 0, v[60:61]
	v_lshl_add_u64 v[60:61], v[60:61], 0, v[126:127]
	v_cvt_pk_bf16_f32 v62, v64, v65
	v_cvt_pk_bf16_f32 v63, v66, v67
	v_cvt_pk_bf16_f32 v64, v78, v79
	v_cvt_pk_bf16_f32 v65, v80, v81
	global_store_dwordx4 v[60:61], v[62:65], off
	v_mul_f32_e32 v67, v70, v174
	v_mul_f32_e32 v66, v74, v174
	v_mul_f32_e32 v63, v68, v174
	v_mul_f32_e32 v62, v72, v174
	v_max_f32_e32 v64, 0, v63
	v_mul_f32_e32 v63, v73, v174
	v_mul_f32_e32 v65, v69, v174
	v_max_f32_e32 v68, 0, v67
	v_mul_f32_e32 v67, v75, v174
	v_mul_f32_e32 v69, v71, v174
	v_max_f32_e32 v62, 0, v62
	v_max_f32_e32 v63, 0, v63
	v_max_f32_e32 v65, 0, v65
	v_max_f32_e32 v66, 0, v66
	v_max_f32_e32 v67, 0, v67
	v_max_f32_e32 v69, 0, v69
	v_pk_mul_f32 v[62:63], v[62:63], v[62:63]
	v_pk_mul_f32 v[64:65], v[64:65], v[64:65]
	v_pk_mul_f32 v[66:67], v[66:67], v[66:67]
	v_pk_mul_f32 v[68:69], v[68:69], v[68:69]
	v_mul_f32_e32 v52, v52, v173
	v_mul_f32_e32 v53, v53, v173
	v_cvt_pk_bf16_f32 v62, v62, v63
	v_cvt_pk_bf16_f32 v63, v66, v67
	v_cvt_pk_bf16_f32 v64, v64, v65
	v_cvt_pk_bf16_f32 v65, v68, v69
	v_max_f32_e32 v52, 0, v52
	v_max_f32_e32 v53, 0, v53
	global_store_dwordx4 v[124:125], v[62:65], off offset:256
	v_mul_f32_e32 v56, v56, v173
	v_mul_f32_e32 v57, v57, v173
	v_pk_mul_f32 v[62:63], v[52:53], v[52:53]
	v_mul_f32_e32 v53, v54, v173
	v_mul_f32_e32 v52, v58, v173
	v_max_f32_e32 v54, 0, v53
	v_mul_f32_e32 v53, v59, v173
	v_mul_f32_e32 v55, v55, v173
	v_max_f32_e32 v56, 0, v56
	v_max_f32_e32 v57, 0, v57
	v_max_f32_e32 v52, 0, v52
	v_max_f32_e32 v53, 0, v53
	v_max_f32_e32 v55, 0, v55
	v_pk_mul_f32 v[56:57], v[56:57], v[56:57]
	v_pk_mul_f32 v[58:59], v[52:53], v[52:53]
	v_pk_mul_f32 v[64:65], v[54:55], v[54:55]
	v_mul_f32_e32 v44, v44, v172
	v_mul_f32_e32 v45, v45, v172
	v_cvt_pk_bf16_f32 v52, v56, v57
	v_cvt_pk_bf16_f32 v53, v58, v59
	v_cvt_pk_bf16_f32 v54, v62, v63
	v_cvt_pk_bf16_f32 v55, v64, v65
	v_max_f32_e32 v44, 0, v44
	v_max_f32_e32 v45, 0, v45
	global_store_dwordx4 v[116:117], v[52:55], off offset:256
	v_mul_f32_e32 v48, v48, v172
	v_mul_f32_e32 v49, v49, v172
	v_pk_mul_f32 v[52:53], v[44:45], v[44:45]
	v_mul_f32_e32 v45, v46, v172
	v_mul_f32_e32 v44, v50, v172
	v_max_f32_e32 v46, 0, v45
	v_mul_f32_e32 v45, v51, v172
	v_mul_f32_e32 v47, v47, v172
	v_max_f32_e32 v48, 0, v48
	v_max_f32_e32 v49, 0, v49
	v_max_f32_e32 v44, 0, v44
	v_max_f32_e32 v45, 0, v45
	v_max_f32_e32 v47, 0, v47
	v_pk_mul_f32 v[48:49], v[48:49], v[48:49]
	v_pk_mul_f32 v[50:51], v[44:45], v[44:45]
	v_pk_mul_f32 v[54:55], v[46:47], v[46:47]
	v_mul_f32_e32 v36, v36, v170
	v_mul_f32_e32 v37, v37, v170
	v_cvt_pk_bf16_f32 v44, v48, v49
	v_cvt_pk_bf16_f32 v45, v50, v51
	v_cvt_pk_bf16_f32 v46, v52, v53
	v_cvt_pk_bf16_f32 v47, v54, v55
	v_max_f32_e32 v36, 0, v36
	v_max_f32_e32 v37, 0, v37
	global_store_dwordx4 v[108:109], v[44:47], off offset:256
	v_mul_f32_e32 v40, v40, v170
	v_mul_f32_e32 v41, v41, v170
	v_pk_mul_f32 v[44:45], v[36:37], v[36:37]
	v_mul_f32_e32 v37, v38, v170
	v_mul_f32_e32 v36, v42, v170
	v_max_f32_e32 v38, 0, v37
	v_mul_f32_e32 v37, v43, v170
	v_mul_f32_e32 v39, v39, v170
	v_max_f32_e32 v40, 0, v40
	v_max_f32_e32 v41, 0, v41
	v_max_f32_e32 v36, 0, v36
	v_max_f32_e32 v37, 0, v37
	v_max_f32_e32 v39, 0, v39
	v_pk_mul_f32 v[40:41], v[40:41], v[40:41]
	v_pk_mul_f32 v[42:43], v[36:37], v[36:37]
	v_pk_mul_f32 v[46:47], v[38:39], v[38:39]
	v_mul_f32_e32 v28, v28, v163
	v_mul_f32_e32 v29, v29, v163
	v_cvt_pk_bf16_f32 v36, v40, v41
	v_cvt_pk_bf16_f32 v37, v42, v43
	v_cvt_pk_bf16_f32 v38, v44, v45
	v_cvt_pk_bf16_f32 v39, v46, v47
	v_max_f32_e32 v28, 0, v28
	v_max_f32_e32 v29, 0, v29
	global_store_dwordx4 v[100:101], v[36:39], off offset:256
	v_mul_f32_e32 v32, v32, v163
	v_mul_f32_e32 v33, v33, v163
	v_pk_mul_f32 v[36:37], v[28:29], v[28:29]
	v_mul_f32_e32 v29, v30, v163
	v_mul_f32_e32 v28, v34, v163
	v_max_f32_e32 v30, 0, v29
	v_mul_f32_e32 v29, v35, v163
	v_mul_f32_e32 v31, v31, v163
	v_max_f32_e32 v32, 0, v32
	v_max_f32_e32 v33, 0, v33
	v_max_f32_e32 v28, 0, v28
	v_max_f32_e32 v29, 0, v29
	v_max_f32_e32 v31, 0, v31
	v_pk_mul_f32 v[32:33], v[32:33], v[32:33]
	v_pk_mul_f32 v[34:35], v[28:29], v[28:29]
	v_pk_mul_f32 v[38:39], v[30:31], v[30:31]
	v_mul_f32_e32 v20, v20, v162
	v_mul_f32_e32 v21, v21, v162
	v_cvt_pk_bf16_f32 v28, v32, v33
	v_cvt_pk_bf16_f32 v29, v34, v35
	v_cvt_pk_bf16_f32 v30, v36, v37
	v_cvt_pk_bf16_f32 v31, v38, v39
	v_max_f32_e32 v20, 0, v20
	v_max_f32_e32 v21, 0, v21
	global_store_dwordx4 v[92:93], v[28:31], off offset:256
	v_mul_f32_e32 v24, v24, v162
	v_mul_f32_e32 v25, v25, v162
	v_pk_mul_f32 v[28:29], v[20:21], v[20:21]
	v_mul_f32_e32 v21, v22, v162
	v_mul_f32_e32 v20, v26, v162
	v_max_f32_e32 v22, 0, v21
	v_mul_f32_e32 v21, v27, v162
	v_mul_f32_e32 v23, v23, v162
	v_max_f32_e32 v24, 0, v24
	v_max_f32_e32 v25, 0, v25
	v_max_f32_e32 v20, 0, v20
	v_max_f32_e32 v21, 0, v21
	v_max_f32_e32 v23, 0, v23
	v_pk_mul_f32 v[24:25], v[24:25], v[24:25]
	v_pk_mul_f32 v[26:27], v[20:21], v[20:21]
	v_pk_mul_f32 v[30:31], v[22:23], v[22:23]
	v_mul_f32_e32 v12, v12, v161
	v_mul_f32_e32 v13, v13, v161
	v_cvt_pk_bf16_f32 v20, v24, v25
	v_cvt_pk_bf16_f32 v21, v26, v27
	v_cvt_pk_bf16_f32 v22, v28, v29
	v_cvt_pk_bf16_f32 v23, v30, v31
	v_max_f32_e32 v12, 0, v12
	v_max_f32_e32 v13, 0, v13
	global_store_dwordx4 v[84:85], v[20:23], off offset:256
	v_mul_f32_e32 v16, v16, v161
	v_mul_f32_e32 v17, v17, v161
	v_pk_mul_f32 v[20:21], v[12:13], v[12:13]
	v_mul_f32_e32 v13, v14, v161
	v_mul_f32_e32 v12, v18, v161
	v_max_f32_e32 v14, 0, v13
	v_mul_f32_e32 v13, v19, v161
	v_mul_f32_e32 v15, v15, v161
	v_max_f32_e32 v16, 0, v16
	v_max_f32_e32 v17, 0, v17
	v_max_f32_e32 v12, 0, v12
	v_max_f32_e32 v13, 0, v13
	v_max_f32_e32 v15, 0, v15
	v_pk_mul_f32 v[16:17], v[16:17], v[16:17]
	v_pk_mul_f32 v[18:19], v[12:13], v[12:13]
	v_pk_mul_f32 v[22:23], v[14:15], v[14:15]
	v_mul_f32_e32 v4, v4, v160
	v_mul_f32_e32 v5, v5, v160
	v_cvt_pk_bf16_f32 v12, v16, v17
	v_cvt_pk_bf16_f32 v13, v18, v19
	v_cvt_pk_bf16_f32 v14, v20, v21
	v_cvt_pk_bf16_f32 v15, v22, v23
	v_max_f32_e32 v4, 0, v4
	v_max_f32_e32 v5, 0, v5
	global_store_dwordx4 v[76:77], v[12:15], off offset:256
	v_mul_f32_e32 v8, v8, v160
	v_mul_f32_e32 v9, v9, v160
	v_pk_mul_f32 v[12:13], v[4:5], v[4:5]
	v_mul_f32_e32 v5, v6, v160
	v_mul_f32_e32 v4, v10, v160
	v_max_f32_e32 v6, 0, v5
	v_mul_f32_e32 v5, v11, v160
	v_mul_f32_e32 v7, v7, v160
	v_max_f32_e32 v8, 0, v8
	v_max_f32_e32 v9, 0, v9
	v_max_f32_e32 v4, 0, v4
	v_max_f32_e32 v5, 0, v5
	v_max_f32_e32 v7, 0, v7
	v_pk_mul_f32 v[8:9], v[8:9], v[8:9]
	v_pk_mul_f32 v[10:11], v[4:5], v[4:5]
	v_pk_mul_f32 v[14:15], v[6:7], v[6:7]
	v_cvt_pk_bf16_f32 v4, v8, v9
	v_cvt_pk_bf16_f32 v5, v10, v11
	v_cvt_pk_bf16_f32 v6, v12, v13
	v_cvt_pk_bf16_f32 v7, v14, v15
	global_store_dwordx4 v[60:61], v[4:7], off offset:256
	s_cbranch_vccz .LBB0_1089
	s_waitcnt vmcnt(0)
	v_mov_b64_e32 v[164:165], 0x100
	v_mov_b64_e32 v[166:167], 0xff
	v_mov_b32_e32 v246, 0
	v_mov_b32_e32 v247, 0
	v_mov_b32_e32 v248, 0
	v_mov_b32_e32 v249, 0
	v_mov_b32_e32 v171, 0x3f2aaaaa
	s_cmpk_gt_u32 s22, 0xff
	v_readlane_b32 s36, v254, 31
	v_readlane_b32 s37, v254, 32
	s_cbranch_scc1 .LBB0_1102
	s_barrier
